# GQA attention loop: LDS-DMA addressing moved from VALU to SALU (byte offsets hoisted, saddr-form global_load_lds, M0 from SGPR adds)
# speedup vs baseline: 1.0242x; 1.0043x over previous
.LBB0_133:
	v_exp_f32_e32 v32, v32
	v_exp_f32_e32 v33, v33
	v_exp_f32_e32 v34, v34
	v_exp_f32_e32 v35, v35
	v_add_f32_e32 v96, 0, v32
	v_exp_f32_e32 v36, v36
	v_add_f32_e32 v96, v33, v96
	v_exp_f32_e32 v37, v37
	v_add_f32_e32 v96, v34, v96
	v_exp_f32_e32 v38, v38
	v_add_f32_e32 v96, v35, v96
	v_exp_f32_e32 v39, v39
	v_add_f32_e32 v96, v36, v96
	v_exp_f32_e32 v40, v40
	v_exp_f32_e32 v48, v48
	v_add_f32_e32 v96, v37, v96
	v_exp_f32_e32 v41, v41
	v_cvt_pk_bf16_f32 v32, v32, v33
	v_cvt_pk_bf16_f32 v33, v34, v35
	v_cvt_pk_bf16_f32 v34, v36, v37
	v_exp_f32_e32 v37, v16
	v_exp_f32_e32 v36, v0
	v_exp_f32_e32 v49, v49
	v_add_f32_e32 v96, v38, v96
	v_exp_f32_e32 v17, v17
	v_exp_f32_e32 v16, v1
	v_exp_f32_e32 v50, v50
	v_add_f32_e32 v96, v39, v96
	v_cvt_pk_bf16_f32 v35, v38, v39
	v_exp_f32_e32 v39, v18
	v_exp_f32_e32 v38, v2
	v_exp_f32_e32 v51, v51
	v_add_f32_e32 v96, v40, v96
	v_exp_f32_e32 v19, v19
	v_exp_f32_e32 v18, v3
	v_add_f32_e32 v97, 0, v48
	v_exp_f32_e32 v52, v52
	v_add_f32_e32 v96, v41, v96
	v_cvt_pk_bf16_f32 v100, v40, v41
	v_pk_add_f32 v[0:1], v[36:37], 0 op_sel_hi:[1,0]
	v_exp_f32_e32 v41, v20
	v_exp_f32_e32 v40, v4
	v_add_f32_e32 v97, v49, v97
	v_exp_f32_e32 v53, v53
	v_pk_add_f32 v[0:1], v[16:17], v[0:1]
	v_exp_f32_e32 v21, v21
	v_exp_f32_e32 v20, v5
	v_add_f32_e32 v97, v50, v97
	v_exp_f32_e32 v54, v54
	v_pk_add_f32 v[0:1], v[38:39], v[0:1]
	v_exp_f32_e32 v5, v22
	v_exp_f32_e32 v4, v6
	v_add_f32_e32 v97, v51, v97
	v_exp_f32_e32 v55, v55
	v_pk_add_f32 v[0:1], v[18:19], v[0:1]
	v_exp_f32_e32 v23, v23
	v_exp_f32_e32 v22, v7
	v_add_f32_e32 v97, v52, v97
	v_exp_f32_e32 v56, v56
	v_exp_f32_e32 v7, v24
	v_exp_f32_e32 v6, v8
	v_pk_add_f32 v[0:1], v[40:41], v[0:1]
	v_add_f32_e32 v97, v53, v97
	v_exp_f32_e32 v57, v57
	v_exp_f32_e32 v25, v25
	v_exp_f32_e32 v24, v9
	v_pk_add_f32 v[0:1], v[20:21], v[0:1]
	v_add_f32_e32 v97, v54, v97
	v_exp_f32_e32 v42, v42
	v_exp_f32_e32 v58, v58
	v_exp_f32_e32 v9, v26
	v_exp_f32_e32 v8, v10
	v_pk_add_f32 v[0:1], v[4:5], v[0:1]
	v_add_f32_e32 v97, v55, v97
	v_exp_f32_e32 v43, v43
	v_exp_f32_e32 v59, v59
	v_exp_f32_e32 v27, v27
	v_exp_f32_e32 v26, v11
	v_pk_add_f32 v[0:1], v[22:23], v[0:1]
	v_add_f32_e32 v97, v56, v97
	v_exp_f32_e32 v44, v44
	v_exp_f32_e32 v60, v60
	v_exp_f32_e32 v11, v28
	v_exp_f32_e32 v10, v12
	v_pk_add_f32 v[0:1], v[6:7], v[0:1]
	v_add_f32_e32 v97, v57, v97
	v_exp_f32_e32 v45, v45
	v_exp_f32_e32 v61, v61
	v_exp_f32_e32 v29, v29
	v_exp_f32_e32 v28, v13
	v_pk_add_f32 v[0:1], v[24:25], v[0:1]
	v_add_f32_e32 v96, v42, v96
	v_add_f32_e32 v97, v58, v97
	v_exp_f32_e32 v46, v46
	v_exp_f32_e32 v62, v62
	v_exp_f32_e32 v13, v30
	v_exp_f32_e32 v12, v14
	v_pk_add_f32 v[0:1], v[8:9], v[0:1]
	v_add_f32_e32 v96, v43, v96
	v_add_f32_e32 v97, v59, v97
	v_exp_f32_e32 v47, v47
	v_exp_f32_e32 v63, v63
	v_exp_f32_e32 v31, v31
	v_exp_f32_e32 v30, v15
	v_pk_add_f32 v[0:1], v[26:27], v[0:1]
	v_add_f32_e32 v96, v44, v96
	v_add_f32_e32 v97, v60, v97
	v_pk_add_f32 v[0:1], v[10:11], v[0:1]
	v_add_f32_e32 v96, v45, v96
	v_add_f32_e32 v97, v61, v97
	v_pk_add_f32 v[0:1], v[28:29], v[0:1]
	v_add_f32_e32 v96, v46, v96
	v_add_f32_e32 v97, v62, v97
	v_pk_add_f32 v[0:1], v[12:13], v[0:1]
	v_add_f32_e32 v96, v47, v96
	v_add_f32_e32 v97, v63, v97
	v_pk_add_f32 v[0:1], v[30:31], v[0:1]
	v_add_f32_e32 v96, v97, v96
	v_add_f32_e32 v0, v0, v1
	v_add_f32_e32 v222, 0, v96
	s_sub_i32 s8, 0x84, s13
	v_add_f32_e32 v227, 0, v0
	v_cvt_pk_bf16_f32 v0, v37, v17
	v_cvt_pk_bf16_f32 v1, v39, v19
	v_cvt_pk_bf16_f32 v2, v41, v21
	v_cvt_pk_bf16_f32 v3, v5, v23
	v_cvt_pk_bf16_f32 v96, v48, v49
	v_cvt_pk_bf16_f32 v97, v50, v51
	v_cvt_pk_bf16_f32 v98, v52, v53
	v_cvt_pk_bf16_f32 v99, v54, v55
	v_cvt_pk_bf16_f32 v101, v42, v43
	v_cvt_pk_bf16_f32 v102, v44, v45
	v_cvt_pk_bf16_f32 v103, v46, v47
	v_cvt_pk_bf16_f32 v104, v56, v57
	v_cvt_pk_bf16_f32 v105, v58, v59
	v_cvt_pk_bf16_f32 v106, v60, v61
	v_cvt_pk_bf16_f32 v107, v62, v63
	v_cvt_pk_bf16_f32 v108, v36, v16
	v_cvt_pk_bf16_f32 v109, v38, v18
	v_cvt_pk_bf16_f32 v110, v40, v20
	v_cvt_pk_bf16_f32 v111, v4, v22
	v_cvt_pk_bf16_f32 v112, v7, v25
	v_cvt_pk_bf16_f32 v113, v9, v27
	v_cvt_pk_bf16_f32 v114, v11, v29
	v_cvt_pk_bf16_f32 v115, v13, v31
	v_cvt_pk_bf16_f32 v116, v6, v24
	v_cvt_pk_bf16_f32 v117, v8, v26
	v_cvt_pk_bf16_f32 v118, v10, v28
	v_cvt_pk_bf16_f32 v119, v12, v30
	s_waitcnt lgkmcnt(0)
	v_mfma_f32_32x32x16_bf16 v[48:63], v[88:91], v[32:35], 0
	s_waitcnt vmcnt(0)
	s_mov_b32 s10, 0
	s_movk_i32 s45, 0x4000
	s_waitcnt vmcnt(0)
	s_barrier
	v_mfma_f32_32x32x16_bf16 v[32:47], v[92:95], v[32:35], 0
	v_mfma_f32_32x32x16_bf16 v[16:31], v[88:91], v[0:3], 0
	v_mfma_f32_32x32x16_bf16 v[0:15], v[92:95], v[0:3], 0
	v_mfma_f32_32x32x16_bf16 v[48:63], v[84:87], v[100:103], v[48:63]
	v_mfma_f32_32x32x16_bf16 v[32:47], v[80:83], v[100:103], v[32:47]
	v_mfma_f32_32x32x16_bf16 v[16:31], v[84:87], v[112:115], v[16:31]
	v_mfma_f32_32x32x16_bf16 v[0:15], v[80:83], v[112:115], v[0:15]
	v_mfma_f32_32x32x16_bf16 v[48:63], v[76:79], v[96:99], v[48:63]
	v_mfma_f32_32x32x16_bf16 v[32:47], v[72:75], v[96:99], v[32:47]
	v_mfma_f32_32x32x16_bf16 v[16:31], v[76:79], v[108:111], v[16:31]
	v_mfma_f32_32x32x16_bf16 v[0:15], v[72:75], v[108:111], v[0:15]
	v_mfma_f32_32x32x16_bf16 v[48:63], v[68:71], v[104:107], v[48:63]
	v_mfma_f32_32x32x16_bf16 v[32:47], v[64:67], v[104:107], v[32:47]
	v_mfma_f32_32x32x16_bf16 v[16:31], v[68:71], v[116:119], v[16:31]
	v_mfma_f32_32x32x16_bf16 v[0:15], v[64:67], v[116:119], v[0:15]
	v_readfirstlane_b32 s98, v213
	v_readfirstlane_b32 s99, v241
	v_lshlrev_b32_e32 v192, 1, v192
	v_lshlrev_b32_e32 v216, 1, v216
	v_lshlrev_b32_e32 v214, 1, v214
	v_lshlrev_b32_e32 v218, 1, v218
	s_branch .LBB0_135

.LBB0_135:
	s_and_b32 s46, s45, 0x4000
	v_add_u32_e32 v188, s46, v242
	v_add_u32_e32 v162, v188, v244
	v_add_u32_e32 v161, v188, v245
	v_add_u32_e32 v160, v188, v246
	v_add_u32_e32 v163, v188, v243
	ds_read_b128 v[164:167], v162
	ds_read_b128 v[168:171], v162 offset:4096
	ds_read_b128 v[172:175], v161
	ds_read_b128 v[176:179], v161 offset:4096
	ds_read_b128 v[180:183], v160
	ds_read_b128 v[184:187], v160 offset:4096
	s_add_i32 s2, s10, 2
	s_cmp_ge_u32 s2, s8
	s_cbranch_scc1 .LBB0_137
	s_add_i32 s2, s13, s10
	s_add_i32 s70, s2, 2
	s_lshl_b64 s[2:3], s[70:71], 13
	s_add_u32 s2, s17, s2
	s_addc_u32 s3, s18, s3
	s_sub_i32 s42, 0x4020, s46
	s_add_i32 s43, s42, s98
	s_mov_b32 m0, s43
	s_add_i32 s42, s42, s99
	global_load_lds_dwordx4 v192, s[2:3]
	s_mov_b32 m0, s42
	s_nop 0
	global_load_lds_dwordx4 v216, s[2:3]
	s_lshl_b64 s[2:3], s[70:71], 7
	s_add_u32 s2, s19, s2
	s_addc_u32 s3, s44, s3
	s_add_i32 m0, s43, 0x2000
	s_addk_i32 s42, 0x2000
	global_load_lds_dwordx4 v214, s[2:3]
	s_mov_b32 m0, s42
	s_nop 0
	global_load_lds_dwordx4 v218, s[2:3]
